# P8 prompt row-pass loads (x, y) non-temporal
# speedup vs baseline: 1.0197x; 1.0022x over previous
; __device__ __forceinline__ float wave_sum(float v) { for (int o = 32; o >= 1; o >>= 1) v += __shfl_xor(v, o); return v; }
; __device__ __forceinline__ f32x4 up4(u32x2 w) { return (f32x4){bf_lo(w.x), bf_hi(w.x), bf_lo(w.y), bf_hi(w.y)}; }
; __device__ __forceinline__ void row_pass1(const Args& a, int row_lo, int row_hi, int gw, int NGW, int lane) {
;     ...
;     for (int r0 = row_lo + 2 * gw; r0 < row_hi; r0 += 2 * NGW) {
;         f32x4 xv[2][4]; u32x2 yv[2][4]; float rs[2];
; #pragma unroll
;         for (int r = 0; r < 2; ++r) { const int row = (r0 + r < row_hi) ? r0 + r : r0; rs[r] = rss[row];
;             const f32x4* xr = (const f32x4*)xrow_ptr(a, row) + lane; const u32x2* yr = (const u32x2*)(Y + (size_t)row * DM) + lane;
; #pragma unroll
;             for (int j = 0; j < 4; ++j) { xv[r][j] = xr[64 * j]; yv[r][j] = yr[64 * j]; } }
; #pragma unroll
;         for (int r = 0; r < 2; ++r) { const int row = r0 + r; if (row >= row_hi) break;
;             const float rstd = rsqrtf(rs[r] * (1.f / DM) + EPS); f32x4 v[4]; float s = 0.f;
; #pragma unroll
;             for (int j = 0; j < 4; ++j) { v[j] = xv[r][j] + up4(yv[r][j]) * rstd * gp[j]; s += (v[j][0] * v[j][0] + v[j][1] * v[j][1]) + (v[j][2] * v[j][2] + v[j][3] * v[j][3]); }
;             const float rstd2 = rsqrtf(wave_sum(s) * (1.f / DM) + EPS);
.LBB0_1040:
	s_add_i32 s3, s8, 1
	s_cmpk_lt_i32 s3, 0x4000
	s_cselect_b32 s0, s3, s8
	s_ashr_i32 s1, s0, 31
	s_lshl_b64 s[28:29], s[0:1], 2
	s_add_u32 s28, s6, s28
	s_addc_u32 s29, s7, s29
	s_add_i32 s30, s0, 0xffffc000
	s_cmpk_lt_i32 s0, 0x4000
	v_readlane_b32 s36, v252, 1
	s_cselect_b32 s31, s1, 0
	s_cselect_b32 s30, s0, s30
	v_readlane_b32 s37, v252, 2
	v_readlane_b32 s38, v252, 3
	v_readlane_b32 s39, v252, 4
	s_cselect_b32 s33, s37, s39
	s_cselect_b32 s34, s36, s38
	s_lshl_b64 s[30:31], s[30:31], 12
	s_add_u32 s30, s34, s30
	v_lshl_add_u64 v[88:89], s[54:55], 0, v[50:51]
	s_addc_u32 s31, s33, s31
	s_lshl_b64 s[0:1], s[0:1], 11
	s_waitcnt vmcnt(6)
	v_add_co_u32_e32 v32, vcc, s11, v88
	s_add_u32 s34, s54, s9
	s_nop 0
	v_addc_co_u32_e32 v33, vcc, 0, v89, vcc
	s_addc_u32 s35, s55, s24
	global_load_dwordx2 v[84:85], v[32:33], off offset:1536 nt
	global_load_dwordx2 v[86:87], v[32:33], off offset:1024 nt
	global_load_dwordx2 v[90:91], v[32:33], off offset:512 nt
	global_load_dwordx2 v[92:93], v[32:33], off nt
	global_load_dword v101, v161, s[34:35]
	v_lshl_add_u64 v[32:33], s[22:23], 0, v[160:161]
	global_load_dwordx4 v[60:63], v[32:33], off nt
	global_load_dwordx4 v[72:75], v[32:33], off offset:1024 nt
	global_load_dwordx4 v[76:79], v[32:33], off offset:2048 nt
	global_load_dwordx4 v[80:83], v[32:33], off offset:3072 nt
	global_load_dword v71, v161, s[28:29]
	v_lshl_add_u64 v[94:95], v[48:49], 0, s[0:1]
	global_load_dwordx4 v[44:47], v160, s[30:31] nt
	global_load_dwordx4 v[40:43], v160, s[30:31] offset:1024 nt
	s_waitcnt lgkmcnt(0)
	global_load_dwordx4 v[36:39], v160, s[30:31] offset:2048 nt
	global_load_dwordx4 v[32:35], v160, s[30:31] offset:3072 nt
	global_load_dwordx2 v[58:59], v[94:95], off nt
	global_load_dwordx2 v[56:57], v[94:95], off offset:512 nt
	global_load_dwordx2 v[54:55], v[94:95], off offset:1024 nt
	global_load_dwordx2 v[52:53], v[94:95], off offset:1536 nt
	s_cmpk_gt_i32 s3, 0x3fff
	v_readlane_b32 s40, v252, 5
	v_readlane_b32 s41, v252, 6
	v_readlane_b32 s42, v252, 7
	v_readlane_b32 s43, v252, 8
	v_readlane_b32 s44, v252, 9
	v_readlane_b32 s45, v252, 10
	v_readlane_b32 s46, v252, 11
	v_readlane_b32 s47, v252, 12
	v_readlane_b32 s48, v252, 13
	v_readlane_b32 s49, v252, 14
	v_readlane_b32 s50, v252, 15
	v_readlane_b32 s51, v252, 16
	s_waitcnt vmcnt(17)
	v_lshlrev_b32_e32 v100, 16, v84
	s_waitcnt vmcnt(16)
	v_lshlrev_b32_e32 v98, 16, v86
	s_waitcnt vmcnt(15)
	v_lshlrev_b32_e32 v96, 16, v90
	s_waitcnt vmcnt(14)
	v_lshlrev_b32_e32 v94, 16, v92
	s_waitcnt vmcnt(13)
	v_fmamk_f32 v101, v101, 0x3a800000, v70
	v_mul_f32_e32 v102, 0x4b800000, v101
	v_cmp_gt_f32_e32 vcc, s25, v101
	v_and_b32_e32 v95, 0xffff0000, v92
	v_lshlrev_b32_e32 v92, 16, v93
	v_cndmask_b32_e32 v101, v101, v102, vcc
	v_rsq_f32_e32 v102, v101
	v_and_b32_e32 v93, 0xffff0000, v93
	v_and_b32_e32 v97, 0xffff0000, v90
	v_lshlrev_b32_e32 v90, 16, v91
	v_mul_f32_e32 v103, 0x45800000, v102
	v_and_b32_e32 v91, 0xffff0000, v91
	v_cndmask_b32_e32 v102, v102, v103, vcc
	v_and_b32_e32 v99, 0xffff0000, v86
	v_lshlrev_b32_e32 v86, 16, v87
	v_and_b32_e32 v87, 0xffff0000, v87
	v_and_b32_e32 v101, 0xffff0000, v84
	v_lshlrev_b32_e32 v84, 16, v85
	v_and_b32_e32 v85, 0xffff0000, v85
	v_pk_mul_f32 v[94:95], v[102:103], v[94:95] op_sel_hi:[0,1]
	v_pk_mul_f32 v[92:93], v[102:103], v[92:93] op_sel_hi:[0,1]
	v_pk_mul_f32 v[96:97], v[102:103], v[96:97] op_sel_hi:[0,1]
	v_pk_mul_f32 v[90:91], v[102:103], v[90:91] op_sel_hi:[0,1]
	v_pk_mul_f32 v[98:99], v[102:103], v[98:99] op_sel_hi:[0,1]
	v_pk_mul_f32 v[104:105], v[102:103], v[86:87] op_sel_hi:[0,1]
	v_pk_mul_f32 v[100:101], v[102:103], v[100:101] op_sel_hi:[0,1]
	v_pk_mul_f32 v[102:103], v[102:103], v[84:85] op_sel_hi:[0,1]
	s_waitcnt vmcnt(12)
	v_pk_fma_f32 v[86:87], v[2:3], v[92:93], v[62:63]
	v_pk_fma_f32 v[84:85], v[0:1], v[94:95], v[60:61]
	s_waitcnt vmcnt(11)
	v_pk_fma_f32 v[74:75], v[10:11], v[90:91], v[74:75]
	v_pk_fma_f32 v[72:73], v[8:9], v[96:97], v[72:73]
	v_pk_mul_f32 v[60:61], v[86:87], v[86:87]
	v_pk_mul_f32 v[62:63], v[84:85], v[84:85]
	v_pk_mul_f32 v[90:91], v[74:75], v[74:75]
	v_pk_mul_f32 v[92:93], v[72:73], v[72:73]
	s_waitcnt vmcnt(10)
	v_pk_fma_f32 v[78:79], v[18:19], v[104:105], v[78:79]
	v_pk_fma_f32 v[76:77], v[16:17], v[98:99], v[76:77]
	v_pk_mov_b32 v[98:99], v[62:63], v[60:61] op_sel:[1,0]
	v_mov_b32_e32 v63, v61
	v_pk_mov_b32 v[60:61], v[92:93], v[90:91] op_sel:[1,0]
	v_mov_b32_e32 v93, v91
	v_mul_f32_e32 v94, v76, v76
	v_mul_f32_e32 v96, v78, v78
	v_pk_add_f32 v[62:63], v[98:99], v[62:63]
	v_pk_add_f32 v[60:61], v[60:61], v[92:93]
	s_waitcnt vmcnt(9)
	v_pk_fma_f32 v[82:83], v[26:27], v[102:103], v[82:83]
	v_pk_fma_f32 v[80:81], v[24:25], v[100:101], v[80:81]
	v_pk_fma_f32 v[90:91], v[76:77], v[76:77], v[94:95] op_sel_hi:[1,1,0]
	v_pk_fma_f32 v[94:95], v[78:79], v[78:79], v[96:97] op_sel_hi:[1,1,0]
	v_pk_add_f32 v[62:63], v[62:63], v[62:63] op_sel_hi:[0,1]
	v_pk_add_f32 v[60:61], v[60:61], v[60:61] op_sel_hi:[0,1]
	v_mul_f32_e32 v90, v80, v80
	v_mul_f32_e32 v94, v81, v81
	v_mul_f32_e32 v62, v82, v82
	v_mul_f32_e32 v60, v83, v83
	v_pk_add_f32 v[90:91], v[90:91], v[94:95]
	v_pk_add_f32 v[60:61], v[62:63], v[60:61]
	v_lshl_add_u64 v[62:63], s[14:15], 0, v[160:161]
	v_pk_add_f32 v[60:61], v[90:91], v[60:61]
	v_add_f32_e32 v60, v60, v61
	ds_bpermute_b32 v61, v64, v60
	s_waitcnt lgkmcnt(0)
	v_add_f32_e32 v60, v60, v61
	ds_bpermute_b32 v61, v65, v60
	s_waitcnt lgkmcnt(0)
	v_add_f32_e32 v60, v60, v61
	ds_bpermute_b32 v61, v66, v60
	s_waitcnt lgkmcnt(0)
	v_add_f32_e32 v60, v60, v61
	ds_bpermute_b32 v61, v67, v60
	s_waitcnt lgkmcnt(0)
	v_add_f32_e32 v60, v60, v61
	ds_bpermute_b32 v61, v68, v60
	s_waitcnt lgkmcnt(0)
; __device__ __forceinline__ float wave_sum(float v) { for (int o = 32; o >= 1; o >>= 1) v += __shfl_xor(v, o); return v; }
; __device__ __forceinline__ u32x2 pk4(f32x4 v) { u32x2 w; w.x = cvt_pk_bf16(v[0], v[1]); w.y = cvt_pk_bf16(v[2], v[3]); return w; }
; __device__ __forceinline__ f32x4 up4(u32x2 w) { return (f32x4){bf_lo(w.x), bf_hi(w.x), bf_lo(w.y), bf_hi(w.y)}; }
; __device__ __forceinline__ void row_pass1(const Args& a, int row_lo, int row_hi, int gw, int NGW, int lane) {
;     ...
;         for (int r = 0; r < 2; ++r) { const int row = r0 + r; if (row >= row_hi) break;
;             const float rstd = rsqrtf(rs[r] * (1.f / DM) + EPS); f32x4 v[4]; float s = 0.f;
; #pragma unroll
;             for (int j = 0; j < 4; ++j) { v[j] = xv[r][j] + up4(yv[r][j]) * rstd * gp[j]; s += (v[j][0] * v[j][0] + v[j][1] * v[j][1]) + (v[j][2] * v[j][2] + v[j][3] * v[j][3]); }
;             const float rstd2 = rsqrtf(wave_sum(s) * (1.f / DM) + EPS);
;             f32x4* xo = (f32x4*)(XO + (size_t)row * DM) + lane; u32x2* ao = (u32x2*)(A2 + (size_t)row * DM) + lane;
; #pragma unroll
;             for (int j = 0; j < 4; ++j) { xo[64 * j] = v[j]; ao[64 * j] = pk4(v[j] * rstd2 * gq[j]); } }
	v_add_f32_e32 v60, v60, v61
	ds_bpermute_b32 v61, v69, v60
	s_waitcnt lgkmcnt(0)
	v_add_f32_e32 v60, v60, v61
	v_fmamk_f32 v60, v60, 0x3a800000, v70
	v_mul_f32_e32 v61, 0x4b800000, v60
	v_cmp_gt_f32_e32 vcc, s25, v60
	s_nop 1
	v_cndmask_b32_e32 v60, v60, v61, vcc
	v_rsq_f32_e32 v90, v60
	v_add_co_u32_e64 v60, s[0:1], s26, v88
	v_mul_f32_e32 v88, 0x45800000, v90
	v_cndmask_b32_e32 v88, v90, v88, vcc
	v_addc_co_u32_e64 v61, s[0:1], 0, v89, s[0:1]
	v_pk_mul_f32 v[84:85], v[84:85], v[88:89] op_sel_hi:[1,0]
	v_pk_mul_f32 v[86:87], v[86:87], v[88:89] op_sel_hi:[1,0]
	v_pk_mul_f32 v[90:91], v[72:73], v[88:89] op_sel_hi:[1,0]
	v_pk_mul_f32 v[92:93], v[74:75], v[88:89] op_sel_hi:[1,0]
	v_pk_mul_f32 v[94:95], v[76:77], v[88:89] op_sel_hi:[1,0]
	v_pk_mul_f32 v[96:97], v[78:79], v[88:89] op_sel_hi:[1,0]
	v_pk_mul_f32 v[98:99], v[80:81], v[88:89] op_sel_hi:[1,0]
	v_pk_mul_f32 v[88:89], v[82:83], v[88:89] op_sel_hi:[1,0]
	v_pk_mul_f32 v[86:87], v[6:7], v[86:87]
	v_pk_mul_f32 v[84:85], v[4:5], v[84:85]
	v_pk_mul_f32 v[92:93], v[14:15], v[92:93]
	v_pk_mul_f32 v[88:89], v[30:31], v[88:89]
	v_pk_mul_f32 v[98:99], v[28:29], v[98:99]
	v_pk_mul_f32 v[90:91], v[12:13], v[90:91]
	v_pk_mul_f32 v[96:97], v[22:23], v[96:97]
	v_pk_mul_f32 v[94:95], v[20:21], v[94:95]
	v_cvt_pk_bf16_f32 v84, v84, v85
	v_cvt_pk_bf16_f32 v85, v86, v87
	v_cvt_pk_bf16_f32 v87, v92, v93
	v_cvt_pk_bf16_f32 v92, v98, v99
	v_cvt_pk_bf16_f32 v93, v88, v89
	v_cvt_pk_bf16_f32 v86, v90, v91
	v_cvt_pk_bf16_f32 v90, v94, v95
	v_cvt_pk_bf16_f32 v91, v96, v97
	global_store_dwordx2 v[60:61], v[84:85], off
	global_store_dwordx2 v[60:61], v[86:87], off offset:512
	global_store_dwordx2 v[60:61], v[90:91], off offset:1024
	global_store_dwordx2 v[60:61], v[92:93], off offset:1536
	s_cbranch_scc1 .LBB0_1039
	s_waitcnt vmcnt(12)
	v_fmamk_f32 v71, v71, 0x3a800000, v70
	v_mul_f32_e32 v72, 0x4b800000, v71
	v_cmp_gt_f32_e32 vcc, s25, v71
	s_waitcnt vmcnt(7)
	v_and_b32_e32 v73, 0xffff0000, v58
	v_lshlrev_b32_e32 v74, 16, v59
	v_cndmask_b32_e32 v71, v71, v72, vcc
	v_rsq_f32_e32 v71, v71
	v_lshlrev_b32_e32 v72, 16, v58
	v_and_b32_e32 v75, 0xffff0000, v59
	v_mul_f32_e32 v58, 0x45800000, v71
	v_cndmask_b32_e32 v58, v71, v58, vcc
	v_pk_mul_f32 v[72:73], v[58:59], v[72:73] op_sel_hi:[0,1]
	v_pk_mul_f32 v[74:75], v[58:59], v[74:75] op_sel_hi:[0,1]
	v_pk_fma_f32 v[46:47], v[2:3], v[74:75], v[46:47]
	v_pk_fma_f32 v[44:45], v[0:1], v[72:73], v[44:45]
	v_pk_mul_f32 v[72:73], v[46:47], v[46:47]
	v_pk_mul_f32 v[74:75], v[44:45], v[44:45]
	s_nop 0
	v_pk_mov_b32 v[76:77], v[74:75], v[72:73] op_sel:[1,0]
	v_mov_b32_e32 v75, v73
	v_pk_add_f32 v[72:73], v[76:77], v[74:75]
	s_waitcnt vmcnt(6)
	v_lshlrev_b32_e32 v74, 16, v56
	v_and_b32_e32 v75, 0xffff0000, v56
	v_lshlrev_b32_e32 v56, 16, v57
	v_and_b32_e32 v57, 0xffff0000, v57
	v_pk_mul_f32 v[74:75], v[58:59], v[74:75] op_sel_hi:[0,1]
	v_pk_mul_f32 v[56:57], v[58:59], v[56:57] op_sel_hi:[0,1]
	v_pk_fma_f32 v[42:43], v[10:11], v[56:57], v[42:43]
	v_pk_fma_f32 v[40:41], v[8:9], v[74:75], v[40:41]
	v_pk_mul_f32 v[56:57], v[42:43], v[42:43]
	v_pk_mul_f32 v[74:75], v[40:41], v[40:41]
	s_nop 0
	v_pk_mov_b32 v[76:77], v[74:75], v[56:57] op_sel:[1,0]
	v_mov_b32_e32 v75, v57
	v_pk_add_f32 v[56:57], v[76:77], v[74:75]
	s_waitcnt vmcnt(5)
	v_lshlrev_b32_e32 v74, 16, v54
	v_and_b32_e32 v75, 0xffff0000, v54
	v_lshlrev_b32_e32 v54, 16, v55
	v_and_b32_e32 v55, 0xffff0000, v55
	v_pk_mul_f32 v[54:55], v[58:59], v[54:55] op_sel_hi:[0,1]
	v_pk_fma_f32 v[38:39], v[18:19], v[54:55], v[38:39]
	s_waitcnt vmcnt(4)
	v_lshlrev_b32_e32 v54, 16, v52
	v_and_b32_e32 v55, 0xffff0000, v52
	v_lshlrev_b32_e32 v52, 16, v53
	v_and_b32_e32 v53, 0xffff0000, v53
	v_pk_mul_f32 v[54:55], v[58:59], v[54:55] op_sel_hi:[0,1]
	v_pk_mul_f32 v[52:53], v[58:59], v[52:53] op_sel_hi:[0,1]
	v_pk_fma_f32 v[32:33], v[24:25], v[54:55], v[32:33]
	v_pk_fma_f32 v[34:35], v[26:27], v[52:53], v[34:35]
	v_mul_f32_e32 v54, v32, v32
	v_pk_add_f32 v[52:53], v[72:73], v[72:73] op_sel:[0,1] op_sel_hi:[1,0]
	v_pk_mul_f32 v[74:75], v[58:59], v[74:75] op_sel_hi:[0,1]
	v_mul_f32_e32 v58, v33, v33
	v_mov_b32_e32 v53, v54
	v_pk_add_f32 v[54:55], v[56:57], v[56:57] op_sel:[0,1] op_sel_hi:[1,0]
	v_pk_fma_f32 v[36:37], v[16:17], v[74:75], v[36:37]
	v_mov_b32_e32 v55, v58
	v_pk_add_f32 v[52:53], v[52:53], v[54:55]
	v_mul_f32_e32 v54, v37, v37
	v_mul_f32_e32 v56, v39, v39
	v_mul_f32_e32 v59, v34, v34
	v_mul_f32_e32 v71, v35, v35
	v_pk_fma_f32 v[54:55], v[36:37], v[36:37], v[54:55] op_sel_hi:[1,1,0]
	v_pk_fma_f32 v[56:57], v[38:39], v[38:39], v[56:57] op_sel_hi:[1,1,0]
	v_mov_b32_e32 v55, v59
	v_mov_b32_e32 v57, v71
	v_pk_add_f32 v[54:55], v[54:55], v[56:57]
	s_nop 0
	v_pk_add_f32 v[52:53], v[52:53], v[54:55]
	s_nop 0
	v_add_f32_e32 v52, v52, v53
	ds_bpermute_b32 v53, v64, v52
	s_waitcnt lgkmcnt(0)
	v_add_f32_e32 v52, v52, v53
	ds_bpermute_b32 v53, v65, v52
	s_waitcnt lgkmcnt(0)
	v_add_f32_e32 v52, v52, v53
	ds_bpermute_b32 v53, v66, v52
	s_waitcnt lgkmcnt(0)
	v_add_f32_e32 v52, v52, v53
	ds_bpermute_b32 v53, v67, v52
	s_waitcnt lgkmcnt(0)
	v_add_f32_e32 v52, v52, v53
	ds_bpermute_b32 v53, v68, v52
	s_waitcnt lgkmcnt(0)
	v_add_f32_e32 v52, v52, v53
	ds_bpermute_b32 v53, v69, v52
	s_waitcnt lgkmcnt(0)
	v_add_f32_e32 v52, v52, v53
	v_fmamk_f32 v52, v52, 0x3a800000, v70
	v_mul_f32_e32 v53, 0x4b800000, v52
	v_cmp_gt_f32_e32 vcc, s25, v52
	s_nop 1
	v_cndmask_b32_e32 v52, v52, v53, vcc
	v_rsq_f32_e32 v52, v52
	s_nop 0
	v_mul_f32_e32 v53, 0x45800000, v52
	v_cndmask_b32_e32 v52, v52, v53, vcc
	v_add_co_u32_e32 v54, vcc, s27, v62
	s_nop 1
	v_addc_co_u32_e32 v55, vcc, 0, v63, vcc
	s_nop 1
	v_pk_mul_f32 v[44:45], v[44:45], v[52:53] op_sel_hi:[1,0]
	v_pk_mul_f32 v[46:47], v[46:47], v[52:53] op_sel_hi:[1,0]
	v_pk_mul_f32 v[44:45], v[4:5], v[44:45]
	v_pk_mul_f32 v[46:47], v[6:7], v[46:47]
	v_cvt_pk_bf16_f32 v44, v44, v45
	v_cvt_pk_bf16_f32 v45, v46, v47
	global_store_dwordx2 v[60:61], v[44:45], off offset:2048
	s_nop 1
	v_pk_mul_f32 v[40:41], v[40:41], v[52:53] op_sel_hi:[1,0]
	v_pk_mul_f32 v[42:43], v[42:43], v[52:53] op_sel_hi:[1,0]
	v_pk_mul_f32 v[40:41], v[12:13], v[40:41]
	v_pk_mul_f32 v[42:43], v[14:15], v[42:43]
	v_cvt_pk_bf16_f32 v40, v40, v41
	v_cvt_pk_bf16_f32 v41, v42, v43
	global_store_dwordx2 v[60:61], v[40:41], off offset:2560
	s_nop 1
	v_pk_mul_f32 v[36:37], v[36:37], v[52:53] op_sel_hi:[1,0]
	v_pk_mul_f32 v[38:39], v[38:39], v[52:53] op_sel_hi:[1,0]
	v_pk_mul_f32 v[36:37], v[20:21], v[36:37]
	v_pk_mul_f32 v[38:39], v[22:23], v[38:39]
	v_cvt_pk_bf16_f32 v36, v36, v37
	v_cvt_pk_bf16_f32 v37, v38, v39
	global_store_dwordx2 v[60:61], v[36:37], off offset:3072
	s_nop 1
	v_pk_mul_f32 v[32:33], v[32:33], v[52:53] op_sel_hi:[1,0]
	v_pk_mul_f32 v[34:35], v[34:35], v[52:53] op_sel_hi:[1,0]
	v_pk_mul_f32 v[32:33], v[28:29], v[32:33]
	v_pk_mul_f32 v[34:35], v[30:31], v[34:35]
	v_cvt_pk_bf16_f32 v32, v32, v33
	v_cvt_pk_bf16_f32 v33, v34, v35
	global_store_dwordx2 v[60:61], v[32:33], off offset:3584
	s_branch .LBB0_1039
